# MLA: first-tile K-fragment LDS reads issued before the stage's global-load address arithmetic
# speedup vs baseline: 1.0164x; 1.0018x over previous
; #define MFMA32(a, b, c) __builtin_amdgcn_mfma_f32_32x32x16_bf16((a), (b), (c), 0, 0, 0)
; #define AT_SB __builtin_amdgcn_sched_barrier(0);
; template <int DQK, int MODE, bool QN, bool KN> ...
;     ...
;   auto compute = [&](int it, int bufi) {
;     const int kt = tile_of(it);
;     const int koff = (kt & 1) * 64;
;     const char* sK = smem + bufi * BUF + koff * KROW;
;     const char* sV = smem + bufi * BUF + KBYTES + koff * 64;
;     bool active = (MODE == 0) || (kt * 64 <= qwmax);
;     if (MODE == 2 && active) active = __builtin_amdgcn_ballot_w64(carry >= 1.17549435e-38f) != 0;
;     if (active) {
;       f32x16 sacc[2];
;       const float sinit = fixed_shift ? -sbound : 0.f;
; #pragma unroll
;       for (int kb = 0; kb < 2; ++kb) {
; #pragma unroll
;         for (int i = 0; i < 16; ++i) sacc[kb][i] = sinit;
; #pragma unroll
;         for (int s = 0; s < NS; ++s) {
;           const bf16x8 kf = *(const bf16x8*)(sK + (kb * 32 + r) * KROW + s * 32 + h * 16);
;           sacc[kb] = MFMA32(kf, qf[s], sacc[kb]);
;         }
;       }
;     ...
;   for (int sg = 0; sg < nsg; sg += 2) {
;     AT_SB AT_GLOAD(rk0, rv0, sg + 2)
;     AT_SB compute(2 * sg, 0); compute(2 * sg + 1, 0); AT_SB
;     AT_SWRITE(rk1, rv1, 1)
;     if (MODE == 2) { if (__syncthreads_and(carry < 1.17549435e-38f)) break; } else { __syncthreads(); }
;     AT_SB AT_GLOAD(rk1, rv1, sg + 3)
.LBB0_1198:
	s_add_i32 s2, s53, 0xffffff01
	v_cmp_le_i32_e64 s[10:11], s2, v243
	s_nop 3
	s_cmp_eq_u64 s[10:11], 0
	s_cbranch_scc1 .Lkh_a
	ds_read_b128 v[32:35], v251
	ds_read_b128 v[36:39], v251 offset:32
	ds_read_b128 v[40:43], v251 offset:64
	ds_read_b128 v[44:47], v251 offset:96
	ds_read_b128 v[48:51], v251 offset:128
	ds_read_b128 v[52:55], v251 offset:160
	ds_read_b128 v[112:115], v251 offset:6656
	ds_read_b128 v[116:119], v251 offset:6688
	ds_read_b128 v[120:123], v251 offset:6720
	ds_read_b128 v[124:127], v251 offset:6752
	ds_read_b128 v[144:147], v251 offset:6784
	ds_read_b128 v[148:151], v251 offset:6816
.Lkh_a:
	s_add_i32 s55, s45, -1
	s_min_i32 s2, s55, s13
	s_lshl_b32 s4, s2, 7
	v_add_u32_e32 v0, s4, v238
	v_mad_i64_i32 v[2:3], s[2:3], v0, s36, v[220:221]
	v_add_u32_e32 v0, s4, v239
	v_mad_i64_i32 v[6:7], s[2:3], v0, s36, v[222:223]
	v_add_u32_e32 v0, s4, v240
	v_mad_i64_i32 v[10:11], s[2:3], v0, s36, v[224:225]
	v_add_u32_e32 v0, s4, v241
	v_mad_i64_i32 v[14:15], s[2:3], v0, s37, v[218:219]
	v_add_u32_e32 v0, s4, v242
	global_load_dwordx4 v[2:5], v[2:3], off
	s_nop 0
	global_load_dwordx4 v[6:9], v[6:7], off
	s_nop 0
	global_load_dwordx4 v[10:13], v[10:11], off
	s_nop 0
	global_load_dwordx4 v[204:207], v[14:15], off
	v_mad_i64_i32 v[14:15], s[2:3], v0, s37, v[218:219]
	global_load_dwordx4 v[208:211], v[14:15], off
	s_add_i32 s2, s53, 0xffffff01
	v_cmp_le_i32_e32 vcc, s2, v243
	s_and_saveexec_b64 s[2:3], vcc
	s_cbranch_execz .LBB0_1208
	s_add_i32 s4, s53, 0xffffff40
	v_cmp_ge_i32_e32 vcc, s4, v236
	s_waitcnt lgkmcnt(11)
	v_mfma_f32_32x32x16_bf16 v[80:95], v[32:35], v[160:163], v[16:31]
	s_waitcnt lgkmcnt(10)
	v_mfma_f32_32x32x16_bf16 v[80:95], v[36:39], v[164:167], v[80:95]
	s_waitcnt lgkmcnt(9)
	v_mfma_f32_32x32x16_bf16 v[80:95], v[40:43], v[168:171], v[80:95]
	s_waitcnt lgkmcnt(8)
	v_mfma_f32_32x32x16_bf16 v[80:95], v[44:47], v[172:175], v[80:95]
	s_waitcnt lgkmcnt(7)
	v_mfma_f32_32x32x16_bf16 v[80:95], v[48:51], v[176:179], v[80:95]
	s_waitcnt lgkmcnt(6)
	v_mfma_f32_32x32x16_bf16 v[80:95], v[52:55], v[180:183], v[80:95]
	s_or_b64 s[10:11], s[0:1], vcc
	s_cbranch_scc0 .Lmfp_0
	s_waitcnt lgkmcnt(5)
	v_mfma_f32_32x32x16_bf16 v[64:79], v[112:115], v[160:163], v[16:31]
	s_waitcnt lgkmcnt(4)
	v_mfma_f32_32x32x16_bf16 v[64:79], v[116:119], v[164:167], v[64:79]
	s_waitcnt lgkmcnt(3)
	v_mfma_f32_32x32x16_bf16 v[64:79], v[120:123], v[168:171], v[64:79]
	s_waitcnt lgkmcnt(2)
	v_mfma_f32_32x32x16_bf16 v[64:79], v[124:127], v[172:175], v[64:79]
	s_waitcnt lgkmcnt(1)
	v_mfma_f32_32x32x16_bf16 v[64:79], v[144:147], v[176:179], v[64:79]
	s_waitcnt lgkmcnt(0)
	v_mfma_f32_32x32x16_bf16 v[64:79], v[148:151], v[180:183], v[64:79]
	s_and_saveexec_b64 s[10:11], vcc
	s_cbranch_execz .LBB0_1201
	v_add_u32_e32 v0, s53, v247
	v_add_u32_e32 v14, 0xffffff01, v0
	v_cmp_lt_i32_e32 vcc, v14, v237
	s_nop 1
	v_cndmask_b32_e32 v81, v234, v81, vcc
	v_cmp_le_i32_e32 vcc, v14, v237
	v_add_u32_e32 v14, 0xffffff03, v0
	s_nop 0
	v_cndmask_b32_e32 v80, v234, v80, vcc
	v_cmp_le_i32_e32 vcc, v14, v237
	v_add_u32_e32 v14, 0xffffff04, v0
	s_nop 0
	v_cndmask_b32_e32 v82, v234, v82, vcc
	v_cmp_le_i32_e32 vcc, v14, v237
	v_add_u32_e32 v14, 0xffffff09, v0
	s_nop 0
	v_cndmask_b32_e32 v83, v234, v83, vcc
	v_cmp_le_i32_e32 vcc, v14, v237
	v_add_u32_e32 v14, 0xffffff0a, v0
	s_nop 0
	v_cndmask_b32_e32 v84, v234, v84, vcc
	v_cmp_le_i32_e32 vcc, v14, v237
	v_add_u32_e32 v14, 0xffffff0b, v0
	s_nop 0
	v_cndmask_b32_e32 v85, v234, v85, vcc
	v_cmp_le_i32_e32 vcc, v14, v237
	v_add_u32_e32 v14, 0xffffff0c, v0
	s_nop 0
	v_cndmask_b32_e32 v86, v234, v86, vcc
	v_cmp_le_i32_e32 vcc, v14, v237
	v_add_u32_e32 v14, 0xffffff11, v0
	s_nop 0
	v_cndmask_b32_e32 v87, v234, v87, vcc
	v_cmp_le_i32_e32 vcc, v14, v237
	v_add_u32_e32 v14, 0xffffff12, v0
	s_nop 0
	v_cndmask_b32_e32 v88, v234, v88, vcc
	v_cmp_le_i32_e32 vcc, v14, v237
	v_add_u32_e32 v14, 0xffffff13, v0
	s_nop 0
	v_cndmask_b32_e32 v89, v234, v89, vcc
	v_cmp_le_i32_e32 vcc, v14, v237
	v_add_u32_e32 v14, 0xffffff14, v0
	s_nop 0
	v_cndmask_b32_e32 v90, v234, v90, vcc
	v_cmp_le_i32_e32 vcc, v14, v237
	v_add_u32_e32 v14, 0xffffff19, v0
	s_nop 0
	v_cndmask_b32_e32 v91, v234, v91, vcc
	v_cmp_le_i32_e32 vcc, v14, v237
	v_add_u32_e32 v14, 0xffffff1a, v0
	s_nop 0
	v_cndmask_b32_e32 v92, v234, v92, vcc
	v_cmp_le_i32_e32 vcc, v14, v237
	v_add_u32_e32 v14, 0xffffff1b, v0
	s_nop 0
	v_cndmask_b32_e32 v93, v234, v93, vcc
	v_cmp_le_i32_e32 vcc, v14, v237
	v_add_u32_e32 v14, 0xffffff1c, v0
	s_nop 0
	v_cndmask_b32_e32 v94, v234, v94, vcc
	v_cmp_le_i32_e32 vcc, v14, v237
	v_add_u32_e32 v14, 0xffffff21, v0
	s_nop 0
	v_cndmask_b32_e32 v95, v234, v95, vcc
	v_cmp_le_i32_e32 vcc, v14, v237
	v_add_u32_e32 v14, 0xffffff22, v0
	s_nop 0
	v_cndmask_b32_e32 v64, v234, v64, vcc
	v_cmp_le_i32_e32 vcc, v14, v237
	v_add_u32_e32 v14, 0xffffff23, v0
	s_nop 0
	v_cndmask_b32_e32 v65, v234, v65, vcc
	v_cmp_le_i32_e32 vcc, v14, v237
	v_add_u32_e32 v14, 0xffffff24, v0
	s_nop 0
	v_cndmask_b32_e32 v66, v234, v66, vcc
	v_cmp_le_i32_e32 vcc, v14, v237
	v_add_u32_e32 v14, 0xffffff29, v0
	s_nop 0
	v_cndmask_b32_e32 v67, v234, v67, vcc
	v_cmp_le_i32_e32 vcc, v14, v237
	v_add_u32_e32 v14, 0xffffff2a, v0
	s_nop 0
	v_cndmask_b32_e32 v68, v234, v68, vcc
	v_cmp_le_i32_e32 vcc, v14, v237
	v_add_u32_e32 v14, 0xffffff2b, v0
	s_nop 0
	v_cndmask_b32_e32 v69, v234, v69, vcc
	v_cmp_le_i32_e32 vcc, v14, v237
	v_add_u32_e32 v14, 0xffffff2c, v0
	s_nop 0
	v_cndmask_b32_e32 v70, v234, v70, vcc
	v_cmp_le_i32_e32 vcc, v14, v237
	v_add_u32_e32 v14, 0xffffff31, v0
	s_nop 0
	v_cndmask_b32_e32 v71, v234, v71, vcc
	v_cmp_le_i32_e32 vcc, v14, v237
	v_add_u32_e32 v14, 0xffffff32, v0
	s_nop 0
	v_cndmask_b32_e32 v72, v234, v72, vcc
	v_cmp_le_i32_e32 vcc, v14, v237
	v_add_u32_e32 v14, 0xffffff33, v0
	s_nop 0
	v_cndmask_b32_e32 v73, v234, v73, vcc
	v_cmp_le_i32_e32 vcc, v14, v237
	v_add_u32_e32 v14, 0xffffff34, v0
	s_nop 0
	v_cndmask_b32_e32 v74, v234, v74, vcc
	v_cmp_le_i32_e32 vcc, v14, v237
	v_add_u32_e32 v14, 0xffffff39, v0
	s_nop 0
	v_cndmask_b32_e32 v75, v234, v75, vcc
	v_cmp_le_i32_e32 vcc, v14, v237
	v_add_u32_e32 v14, 0xffffff3a, v0
	s_nop 0
	v_cndmask_b32_e32 v76, v234, v76, vcc
	v_cmp_le_i32_e32 vcc, v14, v237
	v_add_u32_e32 v14, 0xffffff3b, v0
	v_add_u32_e32 v0, 0xffffff3c, v0
	v_cndmask_b32_e32 v77, v234, v77, vcc
	v_cmp_le_i32_e32 vcc, v14, v237
	s_nop 1
	v_cndmask_b32_e32 v78, v234, v78, vcc
	v_cmp_le_i32_e32 vcc, v0, v237
	s_nop 1
	v_cndmask_b32_e32 v79, v234, v79, vcc

; #define MFMA32(a, b, c) __builtin_amdgcn_mfma_f32_32x32x16_bf16((a), (b), (c), 0, 0, 0)
; #define AT_SB __builtin_amdgcn_sched_barrier(0);
; template <int DQK, int MODE, bool QN, bool KN> ...
;     ...
;   auto compute = [&](int it, int bufi) {
;     const int kt = tile_of(it);
;     const int koff = (kt & 1) * 64;
;     const char* sK = smem + bufi * BUF + koff * KROW;
;     const char* sV = smem + bufi * BUF + KBYTES + koff * 64;
;     bool active = (MODE == 0) || (kt * 64 <= qwmax);
;     if (MODE == 2 && active) active = __builtin_amdgcn_ballot_w64(carry >= 1.17549435e-38f) != 0;
;     if (active) {
;       f32x16 sacc[2];
;       const float sinit = fixed_shift ? -sbound : 0.f;
; #pragma unroll
;       for (int kb = 0; kb < 2; ++kb) {
; #pragma unroll
;         for (int i = 0; i < 16; ++i) sacc[kb][i] = sinit;
; #pragma unroll
;         for (int s = 0; s < NS; ++s) {
;           const bf16x8 kf = *(const bf16x8*)(sK + (kb * 32 + r) * KROW + s * 32 + h * 16);
;           sacc[kb] = MFMA32(kf, qf[s], sacc[kb]);
;         }
;       }
;     ...
;   for (int sg = 0; sg < nsg; sg += 2) {
;     AT_SB AT_GLOAD(rk0, rv0, sg + 2)
;     AT_SB compute(2 * sg, 0); compute(2 * sg + 1, 0); AT_SB
;     AT_SWRITE(rk1, rv1, 1)
;     if (MODE == 2) { if (__syncthreads_and(carry < 1.17549435e-38f)) break; } else { __syncthreads(); }
;     AT_SB AT_GLOAD(rk1, rv1, sg + 3)
;     AT_SB compute(2 * sg + 2, 1); compute(2 * sg + 3, 1); AT_SB
;     AT_SWRITE(rk0, rv0, 0)
;     if (MODE == 2) { if (__syncthreads_and(carry < 1.17549435e-38f)) break; } else { __syncthreads(); }
.LBB0_1218:
	s_or_b64 exec, exec, s[2:3]
	s_waitcnt vmcnt(9)
	ds_write_b128 v244, v[184:187] offset:43008
	s_waitcnt vmcnt(8)
	ds_write_b128 v245, v[188:191] offset:43008
	s_waitcnt vmcnt(7)
	ds_write_b128 v246, v[192:195] offset:43008
	s_waitcnt vmcnt(6)
	ds_write_b128 v250, v[196:199]
	s_waitcnt vmcnt(5)
	ds_write_b128 v250, v[200:203] offset:4096
	s_waitcnt lgkmcnt(0)
	s_barrier
	s_add_i32 s2, s53, 0xffffff81
	v_cmp_le_i32_e64 s[10:11], s2, v243
	s_nop 3
	s_cmp_eq_u64 s[10:11], 0
	s_cbranch_scc1 .Lkh_b
	ds_read_b128 v[32:35], v251 offset:43008
	ds_read_b128 v[36:39], v251 offset:43040
	ds_read_b128 v[40:43], v251 offset:43072
	ds_read_b128 v[44:47], v251 offset:43104
	ds_read_b128 v[48:51], v251 offset:43136
	ds_read_b128 v[52:55], v251 offset:43168
	ds_read_b128 v[112:115], v251 offset:49664
	ds_read_b128 v[116:119], v251 offset:49696
	ds_read_b128 v[120:123], v251 offset:49728
	ds_read_b128 v[124:127], v251 offset:49760
	ds_read_b128 v[144:147], v251 offset:49792
	ds_read_b128 v[148:151], v251 offset:49824
.Lkh_b:
	s_min_i32 s2, s45, s13
	s_lshl_b32 s4, s2, 7
	v_add_u32_e32 v0, s4, v238
	v_mad_i64_i32 v[14:15], s[2:3], v0, s36, v[220:221]
	v_add_u32_e32 v0, s4, v239
	v_mad_i64_i32 v[64:65], s[2:3], v0, s36, v[222:223]
	v_add_u32_e32 v0, s4, v240
	global_load_dwordx4 v[184:187], v[14:15], off
	global_load_dwordx4 v[188:191], v[64:65], off
	v_mad_i64_i32 v[14:15], s[2:3], v0, s36, v[224:225]
	v_add_u32_e32 v0, s4, v241
	v_mad_i64_i32 v[64:65], s[2:3], v0, s37, v[218:219]
	v_add_u32_e32 v0, s4, v242
	global_load_dwordx4 v[192:195], v[14:15], off
	global_load_dwordx4 v[196:199], v[64:65], off
	v_mad_i64_i32 v[14:15], s[2:3], v0, s37, v[218:219]
	global_load_dwordx4 v[200:203], v[14:15], off
	s_add_i32 s2, s53, 0xffffff81
	v_cmp_le_i32_e32 vcc, s2, v243
	s_and_saveexec_b64 s[2:3], vcc
	s_cbranch_execz .LBB0_1228
	s_sub_i32 s4, s53, 64
	v_cmp_ge_i32_e32 vcc, s4, v236
	s_waitcnt lgkmcnt(11)
	v_mfma_f32_32x32x16_bf16 v[80:95], v[32:35], v[160:163], v[16:31]
	s_waitcnt lgkmcnt(10)
	v_mfma_f32_32x32x16_bf16 v[80:95], v[36:39], v[164:167], v[80:95]
	s_waitcnt lgkmcnt(9)
	v_mfma_f32_32x32x16_bf16 v[80:95], v[40:43], v[168:171], v[80:95]
	s_waitcnt lgkmcnt(8)
	v_mfma_f32_32x32x16_bf16 v[80:95], v[44:47], v[172:175], v[80:95]
	s_waitcnt lgkmcnt(7)
	v_mfma_f32_32x32x16_bf16 v[80:95], v[48:51], v[176:179], v[80:95]
	s_waitcnt lgkmcnt(6)
	v_mfma_f32_32x32x16_bf16 v[80:95], v[52:55], v[180:183], v[80:95]
	s_or_b64 s[10:11], s[0:1], vcc
	s_cbranch_scc0 .Lmfp_2
	s_waitcnt lgkmcnt(5)
	v_mfma_f32_32x32x16_bf16 v[64:79], v[112:115], v[160:163], v[16:31]
	s_waitcnt lgkmcnt(4)
	v_mfma_f32_32x32x16_bf16 v[64:79], v[116:119], v[164:167], v[64:79]
	s_waitcnt lgkmcnt(3)
	v_mfma_f32_32x32x16_bf16 v[64:79], v[120:123], v[168:171], v[64:79]
	s_waitcnt lgkmcnt(2)
	v_mfma_f32_32x32x16_bf16 v[64:79], v[124:127], v[172:175], v[64:79]
	s_waitcnt lgkmcnt(1)
	v_mfma_f32_32x32x16_bf16 v[64:79], v[144:147], v[176:179], v[64:79]
	s_waitcnt lgkmcnt(0)
	v_mfma_f32_32x32x16_bf16 v[64:79], v[148:151], v[180:183], v[64:79]
	s_and_saveexec_b64 s[10:11], vcc
	s_cbranch_execz .LBB0_1221
	v_add_u32_e32 v0, s53, v247
	v_add_u32_e32 v14, 0xffffff81, v0
	v_cmp_le_i32_e32 vcc, v14, v237
	v_add_u32_e32 v14, 0xffffff82, v0
	s_nop 0
	v_cndmask_b32_e32 v80, v234, v80, vcc
	v_cmp_le_i32_e32 vcc, v14, v237
	v_add_u32_e32 v14, 0xffffff83, v0
	s_nop 0
	v_cndmask_b32_e32 v81, v234, v81, vcc
	v_cmp_le_i32_e32 vcc, v14, v237
	v_add_u32_e32 v14, 0xffffff84, v0
	s_nop 0
	v_cndmask_b32_e32 v82, v234, v82, vcc
	v_cmp_le_i32_e32 vcc, v14, v237
	v_add_u32_e32 v14, 0xffffff89, v0
	s_nop 0
	v_cndmask_b32_e32 v83, v234, v83, vcc
	v_cmp_le_i32_e32 vcc, v14, v237
	v_add_u32_e32 v14, 0xffffff8a, v0
	s_nop 0
	v_cndmask_b32_e32 v84, v234, v84, vcc
	v_cmp_le_i32_e32 vcc, v14, v237
	v_add_u32_e32 v14, 0xffffff8b, v0
	s_nop 0
	v_cndmask_b32_e32 v85, v234, v85, vcc
	v_cmp_le_i32_e32 vcc, v14, v237
	v_add_u32_e32 v14, 0xffffff8c, v0
	s_nop 0
	v_cndmask_b32_e32 v86, v234, v86, vcc
	v_cmp_le_i32_e32 vcc, v14, v237
	v_add_u32_e32 v14, 0xffffff91, v0
	s_nop 0
	v_cndmask_b32_e32 v87, v234, v87, vcc
	v_cmp_le_i32_e32 vcc, v14, v237
	v_add_u32_e32 v14, 0xffffff92, v0
	s_nop 0
	v_cndmask_b32_e32 v88, v234, v88, vcc
	v_cmp_le_i32_e32 vcc, v14, v237
	v_add_u32_e32 v14, 0xffffff93, v0
	s_nop 0
	v_cndmask_b32_e32 v89, v234, v89, vcc
	v_cmp_le_i32_e32 vcc, v14, v237
	v_add_u32_e32 v14, 0xffffff94, v0
	s_nop 0
	v_cndmask_b32_e32 v90, v234, v90, vcc
	v_cmp_le_i32_e32 vcc, v14, v237
	v_add_u32_e32 v14, 0xffffff99, v0
	s_nop 0
	v_cndmask_b32_e32 v91, v234, v91, vcc
	v_cmp_le_i32_e32 vcc, v14, v237
	v_add_u32_e32 v14, 0xffffff9a, v0
	s_nop 0
	v_cndmask_b32_e32 v92, v234, v92, vcc
	v_cmp_le_i32_e32 vcc, v14, v237
	v_add_u32_e32 v14, 0xffffff9b, v0
	s_nop 0
	v_cndmask_b32_e32 v93, v234, v93, vcc
	v_cmp_le_i32_e32 vcc, v14, v237
	v_add_u32_e32 v14, 0xffffff9c, v0
	s_nop 0
	v_cndmask_b32_e32 v94, v234, v94, vcc
	v_cmp_le_i32_e32 vcc, v14, v237
	v_add_u32_e32 v14, 0xffffffa1, v0
	s_nop 0
	v_cndmask_b32_e32 v95, v234, v95, vcc
	v_cmp_le_i32_e32 vcc, v14, v237
	v_add_u32_e32 v14, 0xffffffa2, v0
	s_nop 0
	v_cndmask_b32_e32 v64, v234, v64, vcc
	v_cmp_le_i32_e32 vcc, v14, v237
	v_add_u32_e32 v14, 0xffffffa3, v0
	s_nop 0
	v_cndmask_b32_e32 v65, v234, v65, vcc
	v_cmp_le_i32_e32 vcc, v14, v237
	v_add_u32_e32 v14, 0xffffffa4, v0
	s_nop 0
	v_cndmask_b32_e32 v66, v234, v66, vcc
	v_cmp_le_i32_e32 vcc, v14, v237
	v_add_u32_e32 v14, 0xffffffa9, v0
	s_nop 0
	v_cndmask_b32_e32 v67, v234, v67, vcc
	v_cmp_le_i32_e32 vcc, v14, v237
	v_add_u32_e32 v14, 0xffffffaa, v0
	s_nop 0
	v_cndmask_b32_e32 v68, v234, v68, vcc
	v_cmp_le_i32_e32 vcc, v14, v237
	v_add_u32_e32 v14, 0xffffffab, v0
	s_nop 0
	v_cndmask_b32_e32 v69, v234, v69, vcc
	v_cmp_le_i32_e32 vcc, v14, v237
	v_add_u32_e32 v14, 0xffffffac, v0
	s_nop 0
	v_cndmask_b32_e32 v70, v234, v70, vcc
	v_cmp_le_i32_e32 vcc, v14, v237
	v_add_u32_e32 v14, 0xffffffb1, v0
	s_nop 0
	v_cndmask_b32_e32 v71, v234, v71, vcc
	v_cmp_le_i32_e32 vcc, v14, v237
	v_add_u32_e32 v14, 0xffffffb2, v0
	s_nop 0
	v_cndmask_b32_e32 v72, v234, v72, vcc
	v_cmp_le_i32_e32 vcc, v14, v237
	v_add_u32_e32 v14, 0xffffffb3, v0
	s_nop 0
	v_cndmask_b32_e32 v73, v234, v73, vcc
	v_cmp_le_i32_e32 vcc, v14, v237
	v_add_u32_e32 v14, 0xffffffb4, v0
	s_nop 0
	v_cndmask_b32_e32 v74, v234, v74, vcc
	v_cmp_le_i32_e32 vcc, v14, v237
	v_add_u32_e32 v14, 0xffffffb9, v0
	s_nop 0
	v_cndmask_b32_e32 v75, v234, v75, vcc
	v_cmp_le_i32_e32 vcc, v14, v237
	v_add_u32_e32 v14, 0xffffffba, v0
	s_nop 0
	v_cndmask_b32_e32 v76, v234, v76, vcc
	v_cmp_le_i32_e32 vcc, v14, v237
	v_add_u32_e32 v14, 0xffffffbb, v0
	v_add_u32_e32 v0, 0xffffffbc, v0
	v_cndmask_b32_e32 v77, v234, v77, vcc
	v_cmp_le_i32_e32 vcc, v14, v237
	s_nop 1
	v_cndmask_b32_e32 v78, v234, v78, vcc
	v_cmp_le_i32_e32 vcc, v0, v237
	s_nop 1
	v_cndmask_b32_e32 v79, v234, v79, vcc
